# final SSM state of the two-chunk sequences computed in the y phase from the tiles it stages (masked slot loads the chunk's own state); the scan phase skips those sequences
# speedup vs baseline: 1.0180x; 1.0180x over previous
.LBB0_2039:
	s_or_b64 exec, exec, s[0:1]
	s_mov_b64 s[6:7], s[60:61]
	s_mov_b64 s[2:3], s[60:61]
	s_mov_b64 s[4:5], s[60:61]
	s_waitcnt lgkmcnt(0)
	v_mov_b32_e32 v0, v219
	s_barrier
	s_mov_b32 s0, 0x240000
	v_readfirstlane_b32 s10, v0
	v_mov_b32_e32 v0, v218
	s_nop 0
	v_lshl_add_u32 v67, s10, 8, v0
	v_cmp_gt_i32_e32 vcc, s0, v67
	s_and_saveexec_b64 s[0:1], vcc
	s_cbranch_execz .LBB0_2046
	s_load_dwordx2 s[6:7], s[6:7], 0xe8
	s_nop 0
	s_load_dwordx2 s[2:3], s[2:3], 0x10
	s_nop 0
	s_load_dwordx2 s[12:13], s[4:5], 0xe0
	v_lshlrev_b32_e32 v0, 3, v0
	v_lshl_add_u32 v71, s10, 11, v0
	s_waitcnt lgkmcnt(0)
	s_add_u32 s4, s6, 0x1108000
	s_addc_u32 s5, s7, 0
	s_add_u32 s6, s12, 0x4000000
	s_addc_u32 s7, s13, 0
	s_and_b64 s[10:11], s[8:9], exec
	s_cselect_b32 s14, 2, 0
	s_mov_b64 s[10:11], 0
	v_readlane_b32 s15, v252, 4
	s_cmp_eq_u32 s15, 0x20000
	s_cbranch_scc0 .LBB0_2042
	v_add_u32_e32 v67, 0x200000, v67
	v_add_u32_e32 v71, 0x1000000, v71
	s_branch .LBB0_2042

.LBB0_2101:
	s_ashr_i32 s12, s13, 3
	s_lshl_b32 s14, s12, 7
	v_add_u32_e32 v0, s14, v170
	v_ashrrev_i32_e32 v1, 31, v0
	v_readlane_b32 s16, v252, 47
	v_writelane_b32 v255, s13, 49
	s_and_b32 s13, s13, 7
	v_lshlrev_b64 v[0:1], 11, v[0:1]
	v_readlane_b32 s17, v252, 48
	v_readlane_b32 s22, v252, 12
	v_readlane_b32 s23, v252, 13
	v_lshl_add_u64 v[0:1], s[16:17], 0, v[0:1]
	s_lshl_b32 s22, s13, 8
	v_lshl_add_u64 v[0:1], v[0:1], 0, s[22:23]
	v_lshlrev_b32_e32 v2, 1, v172
	v_mov_b32_e32 v3, v129
	v_lshl_add_u64 v[0:1], v[0:1], 0, v[2:3]
	global_load_dwordx4 v[130:133], v[0:1], off
	global_load_dwordx4 v[134:137], v[0:1], off offset:32
	global_load_dwordx4 v[138:141], v[0:1], off offset:64
	global_load_dwordx4 v[142:145], v[0:1], off offset:96
	global_load_dwordx4 v[146:149], v[0:1], off offset:128
	global_load_dwordx4 v[150:153], v[0:1], off offset:160
	global_load_dwordx4 v[154:157], v[0:1], off offset:192
	global_load_dwordx4 v[158:161], v[0:1], off offset:224
	v_or_b32_e32 v0, s14, v173
	v_ashrrev_i32_e32 v1, 31, v0
	v_readlane_b32 s16, v252, 45
	v_lshlrev_b64 v[0:1], 11, v[0:1]
	v_readlane_b32 s17, v252, 46
	s_mov_b32 s15, 0x10000
	s_lshl_b32 s13, s13, 2
	v_lshl_add_u64 v[0:1], s[16:17], 0, v[0:1]
	v_lshl_add_u64 v[0:1], v[0:1], 0, s[22:23]
	v_lshl_add_u64 v[64:65], v[0:1], 0, v[2:3]
	v_add_co_u32_e32 v66, vcc, s15, v64
	s_mov_b32 s15, 0x20000
	s_nop 0
	v_addc_co_u32_e32 v67, vcc, 0, v65, vcc
	v_add_co_u32_e32 v68, vcc, s15, v64
	s_mov_b32 s15, 0x30000
	s_nop 0
	v_addc_co_u32_e32 v69, vcc, 0, v65, vcc
	v_add_co_u32_e32 v70, vcc, s15, v64
	v_writelane_b32 v255, s13, 50
	s_nop 0
	v_addc_co_u32_e32 v71, vcc, 0, v65, vcc
	s_ashr_i32 s13, s12, 31
	s_lshl_b64 s[20:21], s[12:13], 19
	v_readlane_b32 s16, v252, 43
	s_add_u32 s15, s16, s20
	v_writelane_b32 v255, s15, 51
	v_readlane_b32 s17, v252, 44
	v_writelane_b32 v255, s20, 52
	s_addc_u32 s15, s17, s21
	s_lshl_b64 s[16:17], s[12:13], 20
	v_writelane_b32 v255, s21, 53
	v_readlane_b32 s20, v252, 49
	v_writelane_b32 v255, s15, 54
	v_readlane_b32 s21, v252, 50
	s_add_u32 s15, s20, s16
	v_writelane_b32 v255, s15, 55
	s_addc_u32 s15, s21, s17
	v_writelane_b32 v255, s15, 56
	s_cmp_lt_u32 s12, 64
	s_cselect_b32 s15, 1, 0
	s_and_b32 s16, s12, 1
	s_xor_b32 s17, s16, 1
	s_and_b32 s17, s17, s15
	s_and_b32 s16, s16, s15
	s_add_i32 s20, s17, -1
	v_writelane_b32 v255, s20, 58
	s_add_i32 s20, s16, -1
	v_writelane_b32 v255, s20, 59
	s_lshl_b32 s20, s17, 1
	s_or_b32 s20, s20, s16
	v_writelane_b32 v255, s20, 63
	s_xor_b32 s20, s16, 1
	s_lshl_b32 s20, s20, 19
	v_writelane_b32 v255, s20, 60
	s_xor_b32 s20, s12, s17
	s_mov_b32 s21, 0
	s_lshl_b64 s[20:21], s[20:21], 19
	v_writelane_b32 v255, s20, 52
	v_writelane_b32 v255, s21, 53
	s_xor_b32 s20, s12, s16
	s_mov_b32 s21, 0
	s_lshl_b64 s[20:21], s[20:21], 20
	s_lshl_b32 s100, s17, 19
	s_add_u32 s20, s20, s100
	s_addc_u32 s21, s21, 0
	v_readlane_b32 s100, v252, 49
	v_readlane_b32 s101, v252, 50
	s_add_u32 s20, s20, s100
	s_addc_u32 s21, s21, s101
	v_writelane_b32 v255, s20, 55
	v_writelane_b32 v255, s21, 56
	s_lshl_b32 s20, s12, 8
	s_lshl_b32 s21, s17, 7
	s_or_b32 s20, s20, s21
	v_writelane_b32 v255, s20, 61
	v_readlane_b32 s21, v252, 32
	s_cmp_lg_u32 s21, 0
	s_cselect_b32 s21, 2, 0
	s_lshr_b32 s20, s12, 1
	s_lshl_b32 s20, s20, 2
	s_or_b32 s20, s20, s21
	s_or_b32 s20, s20, s17
	s_lshl_b32 s20, s20, 20
	s_add_u32 s20, s20, 0x4000000
	v_writelane_b32 v255, s20, 62
	s_mov_b32 s19, 0
	s_lshl_b64 s[12:13], s[12:13], 13
	global_load_dwordx4 v[76:79], v[64:65], off
	global_load_dwordx4 v[80:83], v[66:67], off
	global_load_dwordx4 v[84:87], v[68:69], off
	global_load_dwordx4 v[88:91], v[70:71], off
	global_load_dwordx4 v[92:95], v[64:65], off offset:32
	global_load_dwordx4 v[96:99], v[66:67], off offset:32
	global_load_dwordx4 v[100:103], v[68:69], off offset:32
	global_load_dwordx4 v[104:107], v[70:71], off offset:32
	global_load_dwordx4 v[108:111], v[64:65], off offset:64
	global_load_dwordx4 v[112:115], v[66:67], off offset:64
	global_load_dwordx4 v[116:119], v[68:69], off offset:64
	global_load_dwordx4 v[120:123], v[70:71], off offset:64
	global_load_dwordx4 v[124:127], v[64:65], off offset:96
	global_load_dwordx4 v[72:75], v[66:67], off offset:96
	global_load_dwordx4 v[212:215], v[68:69], off offset:96
	global_load_dwordx4 v[222:225], v[70:71], off offset:96
	global_load_dwordx4 v[234:237], v[64:65], off offset:128
	global_load_dwordx4 v[238:241], v[66:67], off offset:128
	global_load_dwordx4 v[242:245], v[68:69], off offset:128
	global_load_dwordx4 v[246:249], v[70:71], off offset:128
	s_waitcnt vmcnt(19)
	v_mfma_f32_32x32x16_bf16 v[0:15], v[76:79], v[130:133], 0
	global_load_dwordx4 v[76:79], v[64:65], off offset:160
	s_waitcnt vmcnt(19)
	v_mfma_f32_32x32x16_bf16 v[16:31], v[80:83], v[130:133], 0
	global_load_dwordx4 v[80:83], v[66:67], off offset:160
	s_waitcnt vmcnt(19)
	v_mfma_f32_32x32x16_bf16 v[32:47], v[84:87], v[130:133], 0
	global_load_dwordx4 v[84:87], v[68:69], off offset:160
	s_waitcnt vmcnt(19)
	v_mfma_f32_32x32x16_bf16 v[48:63], v[88:91], v[130:133], 0
	global_load_dwordx4 v[88:91], v[70:71], off offset:160
	s_waitcnt vmcnt(19)
	v_mfma_f32_32x32x16_bf16 v[0:15], v[92:95], v[134:137], v[0:15]
	global_load_dwordx4 v[92:95], v[64:65], off offset:192
	s_waitcnt vmcnt(19)
	v_mfma_f32_32x32x16_bf16 v[16:31], v[96:99], v[134:137], v[16:31]
	global_load_dwordx4 v[96:99], v[66:67], off offset:192
	s_waitcnt vmcnt(19)
	v_mfma_f32_32x32x16_bf16 v[32:47], v[100:103], v[134:137], v[32:47]
	global_load_dwordx4 v[100:103], v[68:69], off offset:192
	s_waitcnt vmcnt(19)
	v_mfma_f32_32x32x16_bf16 v[48:63], v[104:107], v[134:137], v[48:63]
	global_load_dwordx4 v[104:107], v[70:71], off offset:192
	s_waitcnt vmcnt(19)
	v_mfma_f32_32x32x16_bf16 v[0:15], v[108:111], v[138:141], v[0:15]
	global_load_dwordx4 v[108:111], v[64:65], off offset:224
	s_waitcnt vmcnt(19)
	v_mfma_f32_32x32x16_bf16 v[16:31], v[112:115], v[138:141], v[16:31]
	global_load_dwordx4 v[112:115], v[66:67], off offset:224
	s_waitcnt vmcnt(19)
	v_mfma_f32_32x32x16_bf16 v[32:47], v[116:119], v[138:141], v[32:47]
	global_load_dwordx4 v[116:119], v[68:69], off offset:224
	s_waitcnt vmcnt(19)
	v_mfma_f32_32x32x16_bf16 v[48:63], v[120:123], v[138:141], v[48:63]
	global_load_dwordx4 v[120:123], v[70:71], off offset:224
	s_waitcnt vmcnt(19)
	v_mfma_f32_32x32x16_bf16 v[0:15], v[124:127], v[142:145], v[0:15]
	s_waitcnt vmcnt(18)
	v_mfma_f32_32x32x16_bf16 v[16:31], v[72:75], v[142:145], v[16:31]
	s_waitcnt vmcnt(17)
	v_mfma_f32_32x32x16_bf16 v[32:47], v[212:215], v[142:145], v[32:47]
	s_waitcnt vmcnt(16)
	v_mfma_f32_32x32x16_bf16 v[48:63], v[222:225], v[142:145], v[48:63]
	s_waitcnt vmcnt(15)
	v_mfma_f32_32x32x16_bf16 v[0:15], v[234:237], v[146:149], v[0:15]
	s_waitcnt vmcnt(14)
	v_mfma_f32_32x32x16_bf16 v[16:31], v[238:241], v[146:149], v[16:31]
	s_waitcnt vmcnt(13)
	v_mfma_f32_32x32x16_bf16 v[32:47], v[242:245], v[146:149], v[32:47]
	s_waitcnt vmcnt(12)
	v_mfma_f32_32x32x16_bf16 v[48:63], v[246:249], v[146:149], v[48:63]
	s_waitcnt vmcnt(11)
	v_mfma_f32_32x32x16_bf16 v[0:15], v[76:79], v[150:153], v[0:15]
	s_waitcnt vmcnt(10)
	v_mfma_f32_32x32x16_bf16 v[16:31], v[80:83], v[150:153], v[16:31]
	s_waitcnt vmcnt(9)
	v_mfma_f32_32x32x16_bf16 v[32:47], v[84:87], v[150:153], v[32:47]
	s_waitcnt vmcnt(8)
	v_mfma_f32_32x32x16_bf16 v[48:63], v[88:91], v[150:153], v[48:63]
	s_waitcnt vmcnt(7)
	v_mfma_f32_32x32x16_bf16 v[0:15], v[92:95], v[154:157], v[0:15]
	s_waitcnt vmcnt(6)
	v_mfma_f32_32x32x16_bf16 v[16:31], v[96:99], v[154:157], v[16:31]
	s_waitcnt vmcnt(5)
	v_mfma_f32_32x32x16_bf16 v[32:47], v[100:103], v[154:157], v[32:47]
	s_waitcnt vmcnt(4)
	v_mfma_f32_32x32x16_bf16 v[48:63], v[104:107], v[154:157], v[48:63]
	s_waitcnt vmcnt(3)
	v_mfma_f32_32x32x16_bf16 v[0:15], v[108:111], v[158:161], v[0:15]
	s_waitcnt vmcnt(2)
	v_mfma_f32_32x32x16_bf16 v[16:31], v[112:115], v[158:161], v[16:31]
	s_waitcnt vmcnt(1)
	v_mfma_f32_32x32x16_bf16 v[32:47], v[116:119], v[158:161], v[32:47]
	s_waitcnt vmcnt(0)
	v_mfma_f32_32x32x16_bf16 v[48:63], v[120:123], v[158:161], v[48:63]
	v_add_u32_e32 v64, s14, v200
	v_ashrrev_i32_e32 v65, 31, v64
	v_readlane_b32 s14, v252, 41
	v_lshlrev_b64 v[64:65], 12, v[64:65]
	v_readlane_b32 s15, v252, 42
	s_nop 1
	v_lshl_add_u64 v[184:185], s[14:15], 0, v[64:65]
	s_branch .LBB0_2103

.LBB0_2103:
	v_writelane_b32 v255, s19, 57
	s_nop 0
	v_readlane_b32 s14, v255, 50
	s_add_i32 s22, s19, s14
	s_lshl_b32 s14, s22, 14
	v_readlane_b32 s15, v255, 51
	s_add_u32 s14, s15, s14
	v_readlane_b32 s15, v255, 54
	s_addc_u32 s15, s15, 0
	s_lshl_b64 s[16:17], s[22:23], 14
	v_readlane_b32 s19, v255, 55
	s_add_u32 s16, s19, s16
	v_readlane_b32 s19, v255, 56
	s_addc_u32 s17, s19, s17
	s_lshl_b64 s[20:21], s[22:23], 13
	v_readlane_b32 vcc_lo, v255, 52
	v_readlane_b32 vcc_hi, v255, 53
	s_add_u32 s20, s20, vcc_lo
	s_addc_u32 s21, s21, vcc_hi
	s_lshl_b64 s[20:21], s[20:21], 1
	v_readlane_b32 s100, v255, 60
	s_or_b32 s19, s20, s100
	v_readlane_b32 vcc_lo, v252, 49
	v_readlane_b32 vcc_hi, v252, 50
	s_add_u32 s20, vcc_lo, s19
	v_lshl_add_u64 v[64:65], s[14:15], 0, v[176:177]
	s_addc_u32 s21, vcc_hi, s21
	s_lshl_b32 s100, s22, 7
	s_add_u32 s100, s100, s12
	s_lshl_b32 s100, s100, 2
	s_mov_b32 s101, 0
	v_lshl_add_u64 v[222:223], s[100:101], 0, v[216:217]
	v_readlane_b32 s100, v252, 49
	v_readlane_b32 s101, v252, 50
	s_add_u32 s100, s100, 0xf7ef8000
	s_addc_u32 s101, s101, -1
	v_readlane_b32 vcc_lo, v255, 61
	s_add_u32 s100, s100, vcc_lo
	s_addc_u32 s101, s101, 0
	s_lshl_b32 vcc_lo, s22, 2
	s_add_u32 s100, s100, vcc_lo
	s_addc_u32 s101, s101, 0
	global_load_dword v251, v129, s[100:101]
	v_readlane_b32 s100, v255, 58
	v_readlane_b32 s101, v255, 59
	global_load_dwordx2 v[224:225], v[222:223], off
	global_load_dwordx4 v[64:67], v[64:65], off
	v_lshl_add_u64 v[68:69], s[16:17], 0, v[176:177]
	global_load_dwordx4 v[68:71], v[68:69], off
	v_lshl_add_u64 v[72:73], s[20:21], 0, v[176:177]
	global_load_dwordx4 v[72:75], v[72:73], off
	v_lshl_add_u64 v[76:77], s[14:15], 0, v[178:179]
	global_load_dwordx4 v[76:79], v[76:77], off
	v_lshl_add_u64 v[80:81], s[16:17], 0, v[178:179]
	global_load_dwordx4 v[80:83], v[80:81], off
	v_lshl_add_u64 v[84:85], s[20:21], 0, v[178:179]
	global_load_dwordx4 v[84:87], v[84:85], off
	v_lshl_add_u64 v[88:89], s[14:15], 0, v[180:181]
	global_load_dwordx4 v[88:91], v[88:89], off
	v_lshl_add_u64 v[92:93], s[16:17], 0, v[180:181]
	global_load_dwordx4 v[92:95], v[92:93], off
	v_lshl_add_u64 v[96:97], s[20:21], 0, v[180:181]
	global_load_dwordx4 v[96:99], v[96:97], off
	v_lshl_add_u64 v[100:101], s[14:15], 0, v[182:183]
	global_load_dwordx4 v[100:103], v[100:101], off
	v_lshl_add_u64 v[104:105], s[16:17], 0, v[182:183]
	global_load_dwordx4 v[104:107], v[104:105], off
	v_lshl_add_u64 v[108:109], s[20:21], 0, v[182:183]
	global_load_dwordx4 v[108:111], v[108:109], off
	v_writelane_b32 v252, s22, 12
	s_lshl_b32 s19, s22, 7
	s_mov_b64 s[14:15], -1
	v_writelane_b32 v252, s23, 13
	s_mov_b32 s20, 0
	s_barrier
	s_waitcnt vmcnt(11)
	ds_write_b64 v226, v[224:225]
	ds_write_b128 v201, v[64:67]
	s_waitcnt vmcnt(10)
	v_and_b32_e32 v222, s100, v68
	v_and_b32_e32 v223, s100, v69
	v_and_b32_e32 v224, s100, v70
	v_and_b32_e32 v225, s100, v71
	ds_write_b128 v201, v[222:225] offset:17408
	s_waitcnt vmcnt(9)
	v_and_b32_e32 v222, s101, v72
	v_and_b32_e32 v223, s101, v73
	v_and_b32_e32 v224, s101, v74
	v_and_b32_e32 v225, s101, v75
	ds_write_b128 v201, v[222:225] offset:34816
	s_waitcnt vmcnt(8)
	ds_write_b128 v202, v[76:79]
	s_waitcnt vmcnt(7)
	v_and_b32_e32 v222, s100, v80
	v_and_b32_e32 v223, s100, v81
	v_and_b32_e32 v224, s100, v82
	v_and_b32_e32 v225, s100, v83
	ds_write_b128 v202, v[222:225] offset:17408
	s_waitcnt vmcnt(6)
	v_and_b32_e32 v222, s101, v84
	v_and_b32_e32 v223, s101, v85
	v_and_b32_e32 v224, s101, v86
	v_and_b32_e32 v225, s101, v87
	ds_write_b128 v202, v[222:225] offset:34816
	s_waitcnt vmcnt(5)
	ds_write_b128 v203, v[88:91]
	s_waitcnt vmcnt(4)
	v_and_b32_e32 v222, s100, v92
	v_and_b32_e32 v223, s100, v93
	v_and_b32_e32 v224, s100, v94
	v_and_b32_e32 v225, s100, v95
	ds_write_b128 v203, v[222:225] offset:17408
	s_waitcnt vmcnt(3)
	v_and_b32_e32 v222, s101, v96
	v_and_b32_e32 v223, s101, v97
	v_and_b32_e32 v224, s101, v98
	v_and_b32_e32 v225, s101, v99
	ds_write_b128 v203, v[222:225] offset:34816
	s_waitcnt vmcnt(2)
	ds_write_b128 v204, v[100:103]
	s_waitcnt vmcnt(1)
	v_and_b32_e32 v222, s100, v104
	v_and_b32_e32 v223, s100, v105
	v_and_b32_e32 v224, s100, v106
	v_and_b32_e32 v225, s100, v107
	ds_write_b128 v204, v[222:225] offset:17408
	s_waitcnt vmcnt(0)
	v_and_b32_e32 v222, s101, v108
	v_and_b32_e32 v223, s101, v109
	v_and_b32_e32 v224, s101, v110
	v_and_b32_e32 v225, s101, v111
	ds_write_b128 v204, v[222:225] offset:34816
	v_readlane_b32 s21, v255, 63
	s_cmp_eq_u32 s21, 0
	s_cbranch_scc1 .Lyo_skip
	v_readlane_b32 s16, v252, 28
	v_readlane_b32 s17, v252, 29
	s_nop 4
	s_load_dwordx2 s[16:17], s[16:17], 0xe0
	v_readlane_b32 vcc_lo, v255, 62
	s_lshl_b32 vcc_hi, s22, 15
	v_readfirstlane_b32 s100, v251
	s_waitcnt lgkmcnt(0)
	s_add_u32 s16, s16, vcc_lo
	s_addc_u32 s17, s17, 0
	s_add_u32 s16, s16, vcc_hi
	s_addc_u32 s17, s17, 0
	s_cmp_eq_u32 s21, 1
	s_cbranch_scc0 .Lyo_even
	v_lshlrev_b32_e32 v251, 1, v176
	v_lshlrev_b32_e32 v64, 16, v72
	v_and_b32_e32 v65, 0xffff0000, v72
	v_lshlrev_b32_e32 v66, 16, v73
	v_and_b32_e32 v67, 0xffff0000, v73
	v_lshlrev_b32_e32 v72, 16, v74
	v_and_b32_e32 v73, 0xffff0000, v74
	v_lshlrev_b32_e32 v74, 16, v75
	v_and_b32_e32 v75, 0xffff0000, v75
	v_lshlrev_b32_e32 v128, 16, v68
	v_fma_f32 v64, s100, v128, v64
	v_and_b32_e32 v128, 0xffff0000, v68
	v_fma_f32 v65, s100, v128, v65
	v_lshlrev_b32_e32 v128, 16, v69
	v_fma_f32 v66, s100, v128, v66
	v_and_b32_e32 v128, 0xffff0000, v69
	v_fma_f32 v67, s100, v128, v67
	v_lshlrev_b32_e32 v128, 16, v70
	v_fma_f32 v72, s100, v128, v72
	v_and_b32_e32 v128, 0xffff0000, v70
	v_fma_f32 v73, s100, v128, v73
	v_lshlrev_b32_e32 v128, 16, v71
	v_fma_f32 v74, s100, v128, v74
	v_and_b32_e32 v128, 0xffff0000, v71
	v_fma_f32 v75, s100, v128, v75
	global_store_dwordx4 v251, v[64:67], s[16:17] nt
	global_store_dwordx4 v251, v[72:75], s[16:17] offset:16 nt
	v_lshlrev_b32_e32 v251, 1, v178
	v_lshlrev_b32_e32 v76, 16, v84
	v_and_b32_e32 v77, 0xffff0000, v84
	v_lshlrev_b32_e32 v78, 16, v85
	v_and_b32_e32 v79, 0xffff0000, v85
	v_lshlrev_b32_e32 v84, 16, v86
	v_and_b32_e32 v85, 0xffff0000, v86
	v_lshlrev_b32_e32 v86, 16, v87
	v_and_b32_e32 v87, 0xffff0000, v87
	v_lshlrev_b32_e32 v128, 16, v80
	v_fma_f32 v76, s100, v128, v76
	v_and_b32_e32 v128, 0xffff0000, v80
	v_fma_f32 v77, s100, v128, v77
	v_lshlrev_b32_e32 v128, 16, v81
	v_fma_f32 v78, s100, v128, v78
	v_and_b32_e32 v128, 0xffff0000, v81
	v_fma_f32 v79, s100, v128, v79
	v_lshlrev_b32_e32 v128, 16, v82
	v_fma_f32 v84, s100, v128, v84
	v_and_b32_e32 v128, 0xffff0000, v82
	v_fma_f32 v85, s100, v128, v85
	v_lshlrev_b32_e32 v128, 16, v83
	v_fma_f32 v86, s100, v128, v86
	v_and_b32_e32 v128, 0xffff0000, v83
	v_fma_f32 v87, s100, v128, v87
	global_store_dwordx4 v251, v[76:79], s[16:17] nt
	global_store_dwordx4 v251, v[84:87], s[16:17] offset:16 nt
	v_lshlrev_b32_e32 v251, 1, v180
	v_lshlrev_b32_e32 v64, 16, v96
	v_and_b32_e32 v65, 0xffff0000, v96
	v_lshlrev_b32_e32 v66, 16, v97
	v_and_b32_e32 v67, 0xffff0000, v97
	v_lshlrev_b32_e32 v96, 16, v98
	v_and_b32_e32 v97, 0xffff0000, v98
	v_lshlrev_b32_e32 v98, 16, v99
	v_and_b32_e32 v99, 0xffff0000, v99
	v_lshlrev_b32_e32 v128, 16, v92
	v_fma_f32 v64, s100, v128, v64
	v_and_b32_e32 v128, 0xffff0000, v92
	v_fma_f32 v65, s100, v128, v65
	v_lshlrev_b32_e32 v128, 16, v93
	v_fma_f32 v66, s100, v128, v66
	v_and_b32_e32 v128, 0xffff0000, v93
	v_fma_f32 v67, s100, v128, v67
	v_lshlrev_b32_e32 v128, 16, v94
	v_fma_f32 v96, s100, v128, v96
	v_and_b32_e32 v128, 0xffff0000, v94
	v_fma_f32 v97, s100, v128, v97
	v_lshlrev_b32_e32 v128, 16, v95
	v_fma_f32 v98, s100, v128, v98
	v_and_b32_e32 v128, 0xffff0000, v95
	v_fma_f32 v99, s100, v128, v99
	global_store_dwordx4 v251, v[64:67], s[16:17] nt
	global_store_dwordx4 v251, v[96:99], s[16:17] offset:16 nt
	v_lshlrev_b32_e32 v251, 1, v182
	v_lshlrev_b32_e32 v76, 16, v108
	v_and_b32_e32 v77, 0xffff0000, v108
	v_lshlrev_b32_e32 v78, 16, v109
	v_and_b32_e32 v79, 0xffff0000, v109
	v_lshlrev_b32_e32 v108, 16, v110
	v_and_b32_e32 v109, 0xffff0000, v110
	v_lshlrev_b32_e32 v110, 16, v111
	v_and_b32_e32 v111, 0xffff0000, v111
	v_lshlrev_b32_e32 v128, 16, v104
	v_fma_f32 v76, s100, v128, v76
	v_and_b32_e32 v128, 0xffff0000, v104
	v_fma_f32 v77, s100, v128, v77
	v_lshlrev_b32_e32 v128, 16, v105
	v_fma_f32 v78, s100, v128, v78
	v_and_b32_e32 v128, 0xffff0000, v105
	v_fma_f32 v79, s100, v128, v79
	v_lshlrev_b32_e32 v128, 16, v106
	v_fma_f32 v108, s100, v128, v108
	v_and_b32_e32 v128, 0xffff0000, v106
	v_fma_f32 v109, s100, v128, v109
	v_lshlrev_b32_e32 v128, 16, v107
	v_fma_f32 v110, s100, v128, v110
	v_and_b32_e32 v128, 0xffff0000, v107
	v_fma_f32 v111, s100, v128, v111
	global_store_dwordx4 v251, v[76:79], s[16:17] nt
	global_store_dwordx4 v251, v[108:111], s[16:17] offset:16 nt
	s_branch .Lyo_skip
.Lyo_even:
	v_lshlrev_b32_e32 v251, 1, v176
	v_lshlrev_b32_e32 v64, 16, v68
	v_and_b32_e32 v65, 0xffff0000, v68
	v_lshlrev_b32_e32 v66, 16, v69
	v_and_b32_e32 v67, 0xffff0000, v69
	v_lshlrev_b32_e32 v68, 16, v70
	v_and_b32_e32 v69, 0xffff0000, v70
	v_lshlrev_b32_e32 v70, 16, v71
	v_and_b32_e32 v71, 0xffff0000, v71
	v_lshlrev_b32_e32 v128, 16, v72
	v_fma_f32 v64, s100, v128, v64
	v_and_b32_e32 v128, 0xffff0000, v72
	v_fma_f32 v65, s100, v128, v65
	v_lshlrev_b32_e32 v128, 16, v73
	v_fma_f32 v66, s100, v128, v66
	v_and_b32_e32 v128, 0xffff0000, v73
	v_fma_f32 v67, s100, v128, v67
	v_lshlrev_b32_e32 v128, 16, v74
	v_fma_f32 v68, s100, v128, v68
	v_and_b32_e32 v128, 0xffff0000, v74
	v_fma_f32 v69, s100, v128, v69
	v_lshlrev_b32_e32 v128, 16, v75
	v_fma_f32 v70, s100, v128, v70
	v_and_b32_e32 v128, 0xffff0000, v75
	v_fma_f32 v71, s100, v128, v71
	global_store_dwordx4 v251, v[64:67], s[16:17] nt
	global_store_dwordx4 v251, v[68:71], s[16:17] offset:16 nt
	v_lshlrev_b32_e32 v251, 1, v178
	v_lshlrev_b32_e32 v76, 16, v80
	v_and_b32_e32 v77, 0xffff0000, v80
	v_lshlrev_b32_e32 v78, 16, v81
	v_and_b32_e32 v79, 0xffff0000, v81
	v_lshlrev_b32_e32 v80, 16, v82
	v_and_b32_e32 v81, 0xffff0000, v82
	v_lshlrev_b32_e32 v82, 16, v83
	v_and_b32_e32 v83, 0xffff0000, v83
	v_lshlrev_b32_e32 v128, 16, v84
	v_fma_f32 v76, s100, v128, v76
	v_and_b32_e32 v128, 0xffff0000, v84
	v_fma_f32 v77, s100, v128, v77
	v_lshlrev_b32_e32 v128, 16, v85
	v_fma_f32 v78, s100, v128, v78
	v_and_b32_e32 v128, 0xffff0000, v85
	v_fma_f32 v79, s100, v128, v79
	v_lshlrev_b32_e32 v128, 16, v86
	v_fma_f32 v80, s100, v128, v80
	v_and_b32_e32 v128, 0xffff0000, v86
	v_fma_f32 v81, s100, v128, v81
	v_lshlrev_b32_e32 v128, 16, v87
	v_fma_f32 v82, s100, v128, v82
	v_and_b32_e32 v128, 0xffff0000, v87
	v_fma_f32 v83, s100, v128, v83
	global_store_dwordx4 v251, v[76:79], s[16:17] nt
	global_store_dwordx4 v251, v[80:83], s[16:17] offset:16 nt
	v_lshlrev_b32_e32 v251, 1, v180
	v_lshlrev_b32_e32 v64, 16, v92
	v_and_b32_e32 v65, 0xffff0000, v92
	v_lshlrev_b32_e32 v66, 16, v93
	v_and_b32_e32 v67, 0xffff0000, v93
	v_lshlrev_b32_e32 v92, 16, v94
	v_and_b32_e32 v93, 0xffff0000, v94
	v_lshlrev_b32_e32 v94, 16, v95
	v_and_b32_e32 v95, 0xffff0000, v95
	v_lshlrev_b32_e32 v128, 16, v96
	v_fma_f32 v64, s100, v128, v64
	v_and_b32_e32 v128, 0xffff0000, v96
	v_fma_f32 v65, s100, v128, v65
	v_lshlrev_b32_e32 v128, 16, v97
	v_fma_f32 v66, s100, v128, v66
	v_and_b32_e32 v128, 0xffff0000, v97
	v_fma_f32 v67, s100, v128, v67
	v_lshlrev_b32_e32 v128, 16, v98
	v_fma_f32 v92, s100, v128, v92
	v_and_b32_e32 v128, 0xffff0000, v98
	v_fma_f32 v93, s100, v128, v93
	v_lshlrev_b32_e32 v128, 16, v99
	v_fma_f32 v94, s100, v128, v94
	v_and_b32_e32 v128, 0xffff0000, v99
	v_fma_f32 v95, s100, v128, v95
	global_store_dwordx4 v251, v[64:67], s[16:17] nt
	global_store_dwordx4 v251, v[92:95], s[16:17] offset:16 nt
	v_lshlrev_b32_e32 v251, 1, v182
	v_lshlrev_b32_e32 v76, 16, v104
	v_and_b32_e32 v77, 0xffff0000, v104
	v_lshlrev_b32_e32 v78, 16, v105
	v_and_b32_e32 v79, 0xffff0000, v105
	v_lshlrev_b32_e32 v104, 16, v106
	v_and_b32_e32 v105, 0xffff0000, v106
	v_lshlrev_b32_e32 v106, 16, v107
	v_and_b32_e32 v107, 0xffff0000, v107
	v_lshlrev_b32_e32 v128, 16, v108
	v_fma_f32 v76, s100, v128, v76
	v_and_b32_e32 v128, 0xffff0000, v108
	v_fma_f32 v77, s100, v128, v77
	v_lshlrev_b32_e32 v128, 16, v109
	v_fma_f32 v78, s100, v128, v78
	v_and_b32_e32 v128, 0xffff0000, v109
	v_fma_f32 v79, s100, v128, v79
	v_lshlrev_b32_e32 v128, 16, v110
	v_fma_f32 v104, s100, v128, v104
	v_and_b32_e32 v128, 0xffff0000, v110
	v_fma_f32 v105, s100, v128, v105
	v_lshlrev_b32_e32 v128, 16, v111
	v_fma_f32 v106, s100, v128, v106
	v_and_b32_e32 v128, 0xffff0000, v111
	v_fma_f32 v107, s100, v128, v107
	global_store_dwordx4 v251, v[76:79], s[16:17] nt
	global_store_dwordx4 v251, v[104:107], s[16:17] offset:16 nt
	s_nop 1
.Lyo_skip:
	v_mov_b32_e32 v78, v129
	v_mov_b32_e32 v79, v129
	v_mov_b32_e32 v64, v129
	v_mov_b32_e32 v65, v129
	v_mov_b32_e32 v66, v129
	v_mov_b32_e32 v67, v129
	v_mov_b32_e32 v68, v129
	v_mov_b32_e32 v69, v129
	v_mov_b32_e32 v70, v129
	v_mov_b32_e32 v71, v129
	v_mov_b32_e32 v72, v129
	v_mov_b32_e32 v73, v129
	v_mov_b32_e32 v74, v129
	v_mov_b32_e32 v75, v129
	v_mov_b32_e32 v76, v129
	v_mov_b32_e32 v77, v129
	v_mov_b64_e32 v[94:95], v[78:79]
	v_mov_b64_e32 v[92:93], v[76:77]
	v_mov_b64_e32 v[90:91], v[74:75]
	v_mov_b64_e32 v[88:89], v[72:73]
	v_mov_b64_e32 v[86:87], v[70:71]
	v_mov_b64_e32 v[84:85], v[68:69]
	v_mov_b64_e32 v[82:83], v[66:67]
	v_mov_b64_e32 v[80:81], v[64:65]
	s_waitcnt lgkmcnt(0)
	s_barrier
	s_branch .LBB0_2105
